# GEMM K-loop static s_setprio 1 moved to the other wave half (s8 != 0) instead of s8 == 0; otherwise identical to v034
# baseline (speedup 1.0000x reference)
; #define PG8_STAGE(bufoff, gbase, voff) do { _Pragma("unroll") for (int _i = 0; _i < 2; ++_i) \
;         __builtin_amdgcn_global_load_lds((const unsigned*)((const char*)(gbase) + (voff)[_i]), (PG8_LAS unsigned*)(lds + (bufoff) + ldsw + _i * 8192), 16, 0, 0); } while (0)
; #define PG8_LDA(dst, b, h) do { _Pragma("unroll") for (int m = 0; m < 4; ++m) _Pragma("unroll") for (int k = 0; k < 2; ++k) dst[m][k] = *(const PG8_LAS bf16x8*)(lds + PG8_SA(b, h) + aoff + m * 2048 + k * 1024); } while (0)
; template <class Epi, class Sched, bool ALIGN_EPI = false, bool SP2 = false>
; __device__ __forceinline__ void gemm_phase(PG8_LAS unsigned char* lds, const Gemm g, const Sched& S, const Epi& E) {
;     ...
;     for (;;) {
;         const bool has_next = S.next(ui + 1, nxt);
;         const char* nA = has_next ? (const char*)g.A + (size_t)nxt.pm * tstep : cA; const char* nB = has_next ? (const char*)g.Bt + (size_t)nxt.pn * tstep : cB;
;         for (int t = 0; t < nt; t += 2) {
;             const bool last = (t == nt - 2);
;             const char* a1 = cA + (size_t)(t + 1) * kstep;
;             const char* a2 = last ? nA : cA + (size_t)(t + 2) * kstep; const char* b2 = last ? nB : cB + (size_t)(t + 2) * kstep;
;             const char* a3 = a2 + kstep; const char* b3 = b2 + kstep;
;             if (last && has_next) S.a_ready(nxt);
;             if constexpr (SP2) {
;             PG8_LDB(B0, 0, 0); PG8_LDB(B1, 0, 1); PG8_SCHED; PG8_LDA(At, 0, 0); PG8_STAGE(PG8_SA(1, 1), a1 + hstep, voffA);
;             PG8_WAIT_V(8); PG8_WAIT_L(0); PG8_BAR; PG8_MMA(0, 0, At, B0); PG8_MMA(0, 1, At, B1); PG8_BAR; PG8_SCHED;
;             PG8_LDA(At, 0, 1); PG8_STAGE(PG8_SB(0, 0), b2, voffB); PG8_STAGE(PG8_SB(0, 1), b2 + hstep, voffB); PG8_STAGE(PG8_SA(0, 0), a2, voffA);
;             PG8_WAIT_V(8); PG8_WAIT_L(0); PG8_BAR; PG8_MMA(1, 0, At, B0); PG8_MMA(1, 1, At, B1); PG8_BAR; PG8_SCHED;
;             PG8_LDB(B0, 1, 0); PG8_LDB(B1, 1, 1); PG8_SCHED; PG8_LDA(At, 1, 0); PG8_STAGE(PG8_SA(0, 1), a2 + hstep, voffA);
;             PG8_WAIT_V(8); PG8_WAIT_L(0); PG8_BAR; PG8_MMA(0, 0, At, B0); PG8_MMA(0, 1, At, B1); PG8_BAR; PG8_SCHED;
;             PG8_LDA(At, 1, 1); PG8_STAGE(PG8_SB(1, 0), b3, voffB); PG8_STAGE(PG8_SB(1, 1), b3 + hstep, voffB); PG8_STAGE(PG8_SA(1, 0), a3, voffA);
;             PG8_WAIT_V(8); PG8_WAIT_L(0); PG8_BAR; PG8_MMA(1, 0, At, B0); PG8_MMA(1, 1, At, B1); PG8_BAR; PG8_SCHED;
.LBB0_643:
	s_cmp_eq_u32 s8, 0
	s_cbranch_scc1 .Lgemm_prio
	s_setprio 1
